# G1 in-proj GEMM K-loop: removed compiler-inserted s_waitcnt vmcnt(0) at loop head (spurious WAW guard on v140)
# speedup vs baseline: 1.0138x; 1.0138x over previous
.LBB0_670:
	s_add_u32 s40, s38, 0xfffc0080
	s_addc_u32 s41, s39, -1
	s_add_i32 s54, 0, 0x10000
	v_add_u32_e32 v140, s54, v145
	ds_read_b128 v[154:157], v140
	ds_read_b128 v[158:161], v140 offset:1024
	ds_read_b128 v[162:165], v140 offset:2048
	ds_read_b128 v[166:169], v140 offset:3072
	s_cmp_eq_u32 s53, 12
	s_cselect_b32 s43, s11, s41
	s_cselect_b32 s42, s17, s40
	s_cselect_b32 s41, s23, s52
	s_cselect_b32 s40, s44, s45
	v_lshl_add_u64 v[142:143], s[38:39], 0, v[136:137]
	s_add_i32 m0, s21, 0xc000
	ds_read_b128 v[170:173], v153
	ds_read_b128 v[174:177], v153 offset:1024
	ds_read_b128 v[188:191], v153 offset:2048
	ds_read_b128 v[192:195], v153 offset:3072
	ds_read_b128 v[196:199], v153 offset:4096
	ds_read_b128 v[200:203], v153 offset:5120
	ds_read_b128 v[204:207], v153 offset:6144
	ds_read_b128 v[208:211], v153 offset:7168
	global_load_lds_dwordx4 v[142:143], off
	v_lshl_add_u64 v[142:143], s[38:39], 0, v[138:139]
	s_add_i32 m0, s21, 0xe000
	s_nop 0
	global_load_lds_dwordx4 v[142:143], off
	s_waitcnt lgkmcnt(8)
	s_barrier
	s_waitcnt lgkmcnt(0)
	s_setprio 1
	s_waitcnt lgkmcnt(0)
	v_mfma_f32_16x16x32_bf16 v[126:129], v[154:157], v[170:173], v[126:129]
	v_mfma_f32_16x16x32_bf16 v[122:125], v[162:165], v[170:173], v[122:125]
	v_mfma_f32_16x16x32_bf16 v[118:121], v[154:157], v[188:191], v[118:121]
	v_mfma_f32_16x16x32_bf16 v[110:113], v[162:165], v[188:191], v[110:113]
	v_mfma_f32_16x16x32_bf16 v[102:105], v[154:157], v[196:199], v[102:105]
	v_mfma_f32_16x16x32_bf16 v[94:97], v[162:165], v[196:199], v[94:97]
	v_mfma_f32_16x16x32_bf16 v[86:89], v[154:157], v[204:207], v[86:89]
	v_mfma_f32_16x16x32_bf16 v[78:81], v[162:165], v[204:207], v[78:81]
	v_mfma_f32_16x16x32_bf16 v[126:129], v[158:161], v[174:177], v[126:129]
	v_mfma_f32_16x16x32_bf16 v[122:125], v[166:169], v[174:177], v[122:125]
	v_mfma_f32_16x16x32_bf16 v[118:121], v[158:161], v[192:195], v[118:121]
	v_mfma_f32_16x16x32_bf16 v[110:113], v[166:169], v[192:195], v[110:113]
	v_mfma_f32_16x16x32_bf16 v[102:105], v[158:161], v[200:203], v[102:105]
	v_mfma_f32_16x16x32_bf16 v[94:97], v[166:169], v[200:203], v[94:97]
	v_mfma_f32_16x16x32_bf16 v[86:89], v[158:161], v[208:211], v[86:89]
	v_mfma_f32_16x16x32_bf16 v[78:81], v[166:169], v[208:211], v[78:81]
	s_setprio 0
	s_barrier
	s_add_i32 s56, 0, 0x14000
	s_add_i32 s54, s54, s20
	v_add_u32_e32 v140, s56, v145
	v_lshl_add_u64 v[142:143], s[40:41], 0, v[16:17]
	s_mov_b32 m0, s54
	ds_read_b128 v[212:215], v140
	ds_read_b128 v[216:219], v140 offset:1024
	ds_read_b128 v[220:223], v140 offset:2048
	ds_read_b128 v[224:227], v140 offset:3072
	global_load_lds_dwordx4 v[142:143], off
	v_lshl_add_u64 v[146:147], s[40:41], 0, v[134:135]
	s_add_i32 m0, s54, 0x2000
	s_nop 0
	global_load_lds_dwordx4 v[146:147], off
	s_barrier
	s_waitcnt lgkmcnt(0)
	s_setprio 1
	s_waitcnt lgkmcnt(0)
	v_mfma_f32_16x16x32_bf16 v[114:117], v[212:215], v[170:173], v[114:117]
	v_mfma_f32_16x16x32_bf16 v[106:109], v[220:223], v[170:173], v[106:109]
	v_mfma_f32_16x16x32_bf16 v[98:101], v[212:215], v[188:191], v[98:101]
	v_mfma_f32_16x16x32_bf16 v[90:93], v[220:223], v[188:191], v[90:93]
	v_mfma_f32_16x16x32_bf16 v[82:85], v[212:215], v[196:199], v[82:85]
	v_mfma_f32_16x16x32_bf16 v[74:77], v[220:223], v[196:199], v[74:77]
	v_mfma_f32_16x16x32_bf16 v[70:73], v[212:215], v[204:207], v[70:73]
	v_mfma_f32_16x16x32_bf16 v[66:69], v[220:223], v[204:207], v[66:69]
	v_mfma_f32_16x16x32_bf16 v[114:117], v[216:219], v[174:177], v[114:117]
	v_mfma_f32_16x16x32_bf16 v[106:109], v[224:227], v[174:177], v[106:109]
	v_mfma_f32_16x16x32_bf16 v[98:101], v[216:219], v[192:195], v[98:101]
	v_mfma_f32_16x16x32_bf16 v[90:93], v[224:227], v[192:195], v[90:93]
	v_mfma_f32_16x16x32_bf16 v[82:85], v[216:219], v[200:203], v[82:85]
	v_mfma_f32_16x16x32_bf16 v[74:77], v[224:227], v[200:203], v[74:77]
	v_mfma_f32_16x16x32_bf16 v[70:73], v[216:219], v[208:211], v[70:73]
	v_mfma_f32_16x16x32_bf16 v[66:69], v[224:227], v[208:211], v[66:69]
	s_setprio 0
	s_mov_b32 m0, s21
	v_lshl_add_u64 v[150:151], s[42:43], 0, v[130:131]
	s_barrier
	ds_read_b128 v[170:173], v153 offset:16384
	ds_read_b128 v[174:177], v153 offset:17408
	ds_read_b128 v[188:191], v153 offset:18432
	ds_read_b128 v[192:195], v153 offset:19456
	ds_read_b128 v[196:199], v153 offset:20480
	ds_read_b128 v[200:203], v153 offset:21504
	ds_read_b128 v[204:207], v153 offset:22528
	ds_read_b128 v[208:211], v153 offset:23552
	global_load_lds_dwordx4 v[150:151], off
	v_lshl_add_u64 v[178:179], s[42:43], 0, v[132:133]
	s_mov_b32 m0, s25
	s_nop 0
	global_load_lds_dwordx4 v[178:179], off
	s_barrier
	s_waitcnt lgkmcnt(0)
	s_setprio 1
	s_waitcnt lgkmcnt(0)
	v_mfma_f32_16x16x32_bf16 v[62:65], v[154:157], v[170:173], v[62:65]
	v_mfma_f32_16x16x32_bf16 v[58:61], v[162:165], v[170:173], v[58:61]
	v_mfma_f32_16x16x32_bf16 v[54:57], v[154:157], v[188:191], v[54:57]
	v_mfma_f32_16x16x32_bf16 v[46:49], v[162:165], v[188:191], v[46:49]
	v_mfma_f32_16x16x32_bf16 v[38:41], v[154:157], v[196:199], v[38:41]
	v_mfma_f32_16x16x32_bf16 v[30:33], v[162:165], v[196:199], v[30:33]
	v_mfma_f32_16x16x32_bf16 v[22:25], v[154:157], v[204:207], v[22:25]
	v_mfma_f32_16x16x32_bf16 v[12:15], v[162:165], v[204:207], v[12:15]
	v_mfma_f32_16x16x32_bf16 v[62:65], v[158:161], v[174:177], v[62:65]
	v_mfma_f32_16x16x32_bf16 v[58:61], v[166:169], v[174:177], v[58:61]
	v_mfma_f32_16x16x32_bf16 v[54:57], v[158:161], v[192:195], v[54:57]
	v_mfma_f32_16x16x32_bf16 v[46:49], v[166:169], v[192:195], v[46:49]
	v_mfma_f32_16x16x32_bf16 v[38:41], v[158:161], v[200:203], v[38:41]
	v_mfma_f32_16x16x32_bf16 v[30:33], v[166:169], v[200:203], v[30:33]
	v_mfma_f32_16x16x32_bf16 v[22:25], v[158:161], v[208:211], v[22:25]
	v_mfma_f32_16x16x32_bf16 v[12:15], v[166:169], v[208:211], v[12:15]
	s_setprio 0
	s_barrier
	s_add_u32 s54, s40, 0x40000
	s_addc_u32 s55, s41, 0
	s_add_i32 s56, s56, s20
	v_lshl_add_u64 v[154:155], s[54:55], 0, v[16:17]
	s_mov_b32 m0, s56
	s_nop 0
	global_load_lds_dwordx4 v[154:155], off
	v_lshl_add_u64 v[154:155], s[54:55], 0, v[134:135]
	s_add_i32 m0, s56, 0x2000
	s_nop 0
	global_load_lds_dwordx4 v[154:155], off
	s_waitcnt vmcnt(6)
	s_barrier
	s_setprio 1
	v_mfma_f32_16x16x32_bf16 v[50:53], v[212:215], v[170:173], v[50:53]
	v_mfma_f32_16x16x32_bf16 v[42:45], v[220:223], v[170:173], v[42:45]
	v_mfma_f32_16x16x32_bf16 v[34:37], v[212:215], v[188:191], v[34:37]
	v_mfma_f32_16x16x32_bf16 v[26:29], v[220:223], v[188:191], v[26:29]
	v_mfma_f32_16x16x32_bf16 v[18:21], v[212:215], v[196:199], v[18:21]
	v_mfma_f32_16x16x32_bf16 v[8:11], v[220:223], v[196:199], v[8:11]
	v_mfma_f32_16x16x32_bf16 v[4:7], v[212:215], v[204:207], v[4:7]
	v_mfma_f32_16x16x32_bf16 v[0:3], v[220:223], v[204:207], v[0:3]
	v_mfma_f32_16x16x32_bf16 v[50:53], v[216:219], v[174:177], v[50:53]
	v_mfma_f32_16x16x32_bf16 v[42:45], v[224:227], v[174:177], v[42:45]
	v_mfma_f32_16x16x32_bf16 v[34:37], v[216:219], v[192:195], v[34:37]
	v_mfma_f32_16x16x32_bf16 v[26:29], v[224:227], v[192:195], v[26:29]
	v_mfma_f32_16x16x32_bf16 v[18:21], v[216:219], v[200:203], v[18:21]
	v_mfma_f32_16x16x32_bf16 v[8:11], v[224:227], v[200:203], v[8:11]
	v_mfma_f32_16x16x32_bf16 v[4:7], v[216:219], v[208:211], v[4:7]
	v_mfma_f32_16x16x32_bf16 v[0:3], v[224:227], v[208:211], v[0:3]
	s_setprio 0
	s_add_i32 s54, 0, 0x18000
	v_add_u32_e32 v140, s54, v145
	s_barrier
	ds_read_b128 v[154:157], v140
	ds_read_b128 v[158:161], v140 offset:1024
	ds_read_b128 v[162:165], v140 offset:2048
	ds_read_b128 v[166:169], v140 offset:3072
	s_add_u32 s42, s42, 0x40000
	s_addc_u32 s43, s43, 0
	s_mov_b32 m0, s33
	v_lshl_add_u64 v[180:181], s[42:43], 0, v[130:131]
	ds_read_b128 v[170:173], v153 offset:32768
	ds_read_b128 v[174:177], v153 offset:33792
	ds_read_b128 v[188:191], v153 offset:34816
	ds_read_b128 v[192:195], v153 offset:35840
	ds_read_b128 v[196:199], v153 offset:36864
	ds_read_b128 v[200:203], v153 offset:37888
	ds_read_b128 v[204:207], v153 offset:38912
	ds_read_b128 v[208:211], v153 offset:39936
	global_load_lds_dwordx4 v[180:181], off
	v_lshl_add_u64 v[180:181], s[42:43], 0, v[132:133]
	s_mov_b32 m0, s35
	s_nop 0
	global_load_lds_dwordx4 v[180:181], off
	s_waitcnt lgkmcnt(8)
	s_barrier
	s_waitcnt lgkmcnt(0)
	s_setprio 1
	s_waitcnt lgkmcnt(0)
	v_mfma_f32_16x16x32_bf16 v[126:129], v[154:157], v[170:173], v[126:129]
	v_mfma_f32_16x16x32_bf16 v[122:125], v[162:165], v[170:173], v[122:125]
	v_mfma_f32_16x16x32_bf16 v[118:121], v[154:157], v[188:191], v[118:121]
	v_mfma_f32_16x16x32_bf16 v[110:113], v[162:165], v[188:191], v[110:113]
	v_mfma_f32_16x16x32_bf16 v[102:105], v[154:157], v[196:199], v[102:105]
	v_mfma_f32_16x16x32_bf16 v[94:97], v[162:165], v[196:199], v[94:97]
	v_mfma_f32_16x16x32_bf16 v[86:89], v[154:157], v[204:207], v[86:89]
	v_mfma_f32_16x16x32_bf16 v[78:81], v[162:165], v[204:207], v[78:81]
	v_mfma_f32_16x16x32_bf16 v[126:129], v[158:161], v[174:177], v[126:129]
	v_mfma_f32_16x16x32_bf16 v[122:125], v[166:169], v[174:177], v[122:125]
	v_mfma_f32_16x16x32_bf16 v[118:121], v[158:161], v[192:195], v[118:121]
	v_mfma_f32_16x16x32_bf16 v[110:113], v[166:169], v[192:195], v[110:113]
	v_mfma_f32_16x16x32_bf16 v[102:105], v[158:161], v[200:203], v[102:105]
	v_mfma_f32_16x16x32_bf16 v[94:97], v[166:169], v[200:203], v[94:97]
	v_mfma_f32_16x16x32_bf16 v[86:89], v[158:161], v[208:211], v[86:89]
	v_mfma_f32_16x16x32_bf16 v[78:81], v[166:169], v[208:211], v[78:81]
	s_setprio 0
	s_barrier
	s_add_i32 s42, 0, 0x1c000
	s_add_i32 s43, s54, s20
	v_add_u32_e32 v140, s42, v145
	v_lshl_add_u64 v[142:143], v[142:143], 0, s[14:15]
	s_mov_b32 m0, s43
	ds_read_b128 v[212:215], v140
	ds_read_b128 v[216:219], v140 offset:1024
	ds_read_b128 v[220:223], v140 offset:2048
	ds_read_b128 v[224:227], v140 offset:3072
	global_load_lds_dwordx4 v[142:143], off
	v_lshl_add_u64 v[142:143], v[146:147], 0, s[14:15]
	s_add_i32 m0, s43, 0x2000
	s_nop 0
	global_load_lds_dwordx4 v[142:143], off
	s_barrier
	s_waitcnt lgkmcnt(0)
	s_setprio 1
	s_waitcnt lgkmcnt(0)
	v_mfma_f32_16x16x32_bf16 v[114:117], v[212:215], v[170:173], v[114:117]
	v_mfma_f32_16x16x32_bf16 v[106:109], v[220:223], v[170:173], v[106:109]
	v_mfma_f32_16x16x32_bf16 v[98:101], v[212:215], v[188:191], v[98:101]
	v_mfma_f32_16x16x32_bf16 v[90:93], v[220:223], v[188:191], v[90:93]
	v_mfma_f32_16x16x32_bf16 v[82:85], v[212:215], v[196:199], v[82:85]
	v_mfma_f32_16x16x32_bf16 v[74:77], v[220:223], v[196:199], v[74:77]
	v_mfma_f32_16x16x32_bf16 v[70:73], v[212:215], v[204:207], v[70:73]
	v_mfma_f32_16x16x32_bf16 v[66:69], v[220:223], v[204:207], v[66:69]
	v_mfma_f32_16x16x32_bf16 v[114:117], v[216:219], v[174:177], v[114:117]
	v_mfma_f32_16x16x32_bf16 v[106:109], v[224:227], v[174:177], v[106:109]
	v_mfma_f32_16x16x32_bf16 v[98:101], v[216:219], v[192:195], v[98:101]
	v_mfma_f32_16x16x32_bf16 v[90:93], v[224:227], v[192:195], v[90:93]
	v_mfma_f32_16x16x32_bf16 v[82:85], v[216:219], v[200:203], v[82:85]
	v_mfma_f32_16x16x32_bf16 v[74:77], v[224:227], v[200:203], v[74:77]
	v_mfma_f32_16x16x32_bf16 v[70:73], v[216:219], v[208:211], v[70:73]
	v_mfma_f32_16x16x32_bf16 v[66:69], v[224:227], v[208:211], v[66:69]
	s_setprio 0
	s_mov_b32 m0, s46
	v_lshl_add_u64 v[142:143], v[150:151], 0, s[14:15]
	s_barrier
	ds_read_b128 v[170:173], v153 offset:49152
	ds_read_b128 v[174:177], v153 offset:50176
	ds_read_b128 v[188:191], v153 offset:51200
	ds_read_b128 v[192:195], v153 offset:52224
	ds_read_b128 v[196:199], v153 offset:53248
	ds_read_b128 v[200:203], v153 offset:54272
	ds_read_b128 v[204:207], v153 offset:55296
	ds_read_b128 v[208:211], v153 offset:56320
	global_load_lds_dwordx4 v[142:143], off
	v_lshl_add_u64 v[142:143], v[178:179], 0, s[14:15]
	s_mov_b32 m0, s47
	s_nop 0
	global_load_lds_dwordx4 v[142:143], off
	s_barrier
	s_waitcnt lgkmcnt(0)
	s_setprio 1
	s_waitcnt lgkmcnt(0)
	v_mfma_f32_16x16x32_bf16 v[62:65], v[154:157], v[170:173], v[62:65]
	v_mfma_f32_16x16x32_bf16 v[58:61], v[162:165], v[170:173], v[58:61]
	v_mfma_f32_16x16x32_bf16 v[54:57], v[154:157], v[188:191], v[54:57]
	v_mfma_f32_16x16x32_bf16 v[46:49], v[162:165], v[188:191], v[46:49]
	v_mfma_f32_16x16x32_bf16 v[38:41], v[154:157], v[196:199], v[38:41]
	v_mfma_f32_16x16x32_bf16 v[30:33], v[162:165], v[196:199], v[30:33]
	v_mfma_f32_16x16x32_bf16 v[22:25], v[154:157], v[204:207], v[22:25]
	v_mfma_f32_16x16x32_bf16 v[12:15], v[162:165], v[204:207], v[12:15]
	v_mfma_f32_16x16x32_bf16 v[62:65], v[158:161], v[174:177], v[62:65]
	v_mfma_f32_16x16x32_bf16 v[58:61], v[166:169], v[174:177], v[58:61]
	v_mfma_f32_16x16x32_bf16 v[54:57], v[158:161], v[192:195], v[54:57]
	v_mfma_f32_16x16x32_bf16 v[46:49], v[166:169], v[192:195], v[46:49]
	v_mfma_f32_16x16x32_bf16 v[38:41], v[158:161], v[200:203], v[38:41]
	v_mfma_f32_16x16x32_bf16 v[30:33], v[166:169], v[200:203], v[30:33]
	v_mfma_f32_16x16x32_bf16 v[22:25], v[158:161], v[208:211], v[22:25]
	v_mfma_f32_16x16x32_bf16 v[12:15], v[166:169], v[208:211], v[12:15]
	s_setprio 0
	s_barrier
	s_add_u32 s40, s40, 0x40080
	s_addc_u32 s41, s41, 0
	s_add_i32 s42, s42, s20
	v_lshl_add_u64 v[142:143], s[40:41], 0, v[16:17]
	s_mov_b32 m0, s42
	s_nop 0
	global_load_lds_dwordx4 v[142:143], off
	v_lshl_add_u64 v[142:143], s[40:41], 0, v[134:135]
	s_add_i32 m0, s42, 0x2000
	s_nop 0
	global_load_lds_dwordx4 v[142:143], off
	s_waitcnt vmcnt(6)
	s_barrier
	s_setprio 1
	v_mfma_f32_16x16x32_bf16 v[50:53], v[212:215], v[170:173], v[50:53]
	v_mfma_f32_16x16x32_bf16 v[42:45], v[220:223], v[170:173], v[42:45]
	v_mfma_f32_16x16x32_bf16 v[34:37], v[212:215], v[188:191], v[34:37]
	v_mfma_f32_16x16x32_bf16 v[26:29], v[220:223], v[188:191], v[26:29]
	v_mfma_f32_16x16x32_bf16 v[18:21], v[212:215], v[196:199], v[18:21]
	v_mfma_f32_16x16x32_bf16 v[8:11], v[220:223], v[196:199], v[8:11]
	v_mfma_f32_16x16x32_bf16 v[4:7], v[212:215], v[204:207], v[4:7]
	v_mfma_f32_16x16x32_bf16 v[0:3], v[220:223], v[204:207], v[0:3]
	v_mfma_f32_16x16x32_bf16 v[50:53], v[216:219], v[174:177], v[50:53]
	v_mfma_f32_16x16x32_bf16 v[42:45], v[224:227], v[174:177], v[42:45]
	v_mfma_f32_16x16x32_bf16 v[34:37], v[216:219], v[192:195], v[34:37]
	v_mfma_f32_16x16x32_bf16 v[26:29], v[224:227], v[192:195], v[26:29]
	v_mfma_f32_16x16x32_bf16 v[18:21], v[216:219], v[200:203], v[18:21]
	v_mfma_f32_16x16x32_bf16 v[8:11], v[224:227], v[200:203], v[8:11]
	v_mfma_f32_16x16x32_bf16 v[4:7], v[216:219], v[208:211], v[4:7]
	v_mfma_f32_16x16x32_bf16 v[0:3], v[224:227], v[208:211], v[0:3]
	s_setprio 0
	s_add_i32 s53, s53, 2
	s_add_u32 s38, s38, 0x100
	s_addc_u32 s39, s39, 0
	s_add_u32 s45, s45, 0x100
	s_addc_u32 s52, s52, 0
	s_cmp_gt_u32 s53, 13
	s_barrier
	s_cbranch_scc0 .LBB0_670
	v_lshl_add_u32 v168, s34, 8, v141
	v_readlane_b32 s38, v252, 38
	v_ashrrev_i32_e32 v169, 31, v168
	v_or_b32_e32 v164, 16, v168
	v_or_b32_e32 v160, 32, v168
	v_or_b32_e32 v154, 48, v168
	v_readlane_b32 s39, v252, 39
	v_ashrrev_i32_e32 v165, 31, v164
	v_ashrrev_i32_e32 v161, 31, v160
	v_ashrrev_i32_e32 v155, 31, v154
	v_lshl_add_u64 v[142:143], v[168:169], 2, s[38:39]
	v_lshl_add_u64 v[146:147], v[164:165], 2, s[38:39]
	v_lshl_add_u64 v[150:151], v[160:161], 2, s[38:39]
	v_lshl_add_u64 v[156:157], v[154:155], 2, s[38:39]
	global_load_dword v170, v[142:143], off
	global_load_dword v166, v[146:147], off
	global_load_dword v162, v[150:151], off
	global_load_dword v158, v[156:157], off
	global_load_dword v152, v[142:143], off offset:512
	global_load_dword v148, v[142:143], off offset:576
	global_load_dword v144, v[142:143], off offset:640
	global_load_dword v140, v[142:143], off offset:704
	v_add_u32_e32 v156, 0x80, v168
	v_add_u32_e32 v150, 0x90, v168
	v_add_u32_e32 v146, 0xa0, v168
	v_add_u32_e32 v142, 0xb0, v168
	v_lshl_or_b32 v172, s22, 8, v149
	s_cmp_eq_u32 s51, 0
	v_ashrrev_i32_e32 v157, 31, v156
	v_ashrrev_i32_e32 v151, 31, v150
	v_ashrrev_i32_e32 v147, 31, v146
	v_ashrrev_i32_e32 v143, 31, v142
	v_ashrrev_i32_e32 v173, 31, v172
	s_cbranch_scc1 .LBB0_673
	s_waitcnt vmcnt(0)
	v_mul_f32_e32 v176, v124, v170
	v_mul_f32_e32 v176, 0xbfb8aa3b, v176
	v_exp_f32_e32 v176, v176
	v_mul_f32_e32 v159, v126, v170
	v_mul_f32_e32 v167, v127, v170
	v_lshlrev_b64 v[174:175], 12, v[168:169]
	v_mul_f32_e32 v159, 0xbfb8aa3b, v159
	v_mul_f32_e32 v163, v122, v170
	v_mul_f32_e32 v167, 0xbfb8aa3b, v167
	v_mul_f32_e32 v169, v123, v170
	v_mul_f32_e32 v171, v128, v170
	v_add_f32_e32 v176, 1.0, v176
	v_mul_f32_e32 v177, v129, v170
	v_exp_f32_e32 v159, v159
	v_mul_f32_e32 v163, 0xbfb8aa3b, v163
	v_exp_f32_e32 v167, v167
	v_mul_f32_e32 v169, 0xbfb8aa3b, v169
	v_mul_f32_e32 v171, 0xbfb8aa3b, v171
	v_rcp_f32_e32 v176, v176
	v_mul_f32_e32 v177, 0xbfb8aa3b, v177
	v_mul_f32_e32 v178, v125, v170
	v_exp_f32_e32 v163, v163
	v_exp_f32_e32 v169, v169
	v_exp_f32_e32 v171, v171
	v_exp_f32_e32 v177, v177
	v_mul_f32_e32 v178, 0xbfb8aa3b, v178
	v_exp_f32_e32 v178, v178
	v_add_f32_e32 v159, 1.0, v159
	v_add_f32_e32 v167, 1.0, v167
	v_fma_f32 v176, v176, s31, 0.5
	v_rcp_f32_e32 v159, v159
	v_add_f32_e32 v163, 1.0, v163
	v_rcp_f32_e32 v167, v167
	v_add_f32_e32 v169, 1.0, v169
	v_add_f32_e32 v171, 1.0, v171
	v_max_f32_e32 v176, 1.0, v176
	v_add_f32_e32 v177, 1.0, v177
	v_rcp_f32_e32 v163, v163
	v_rcp_f32_e32 v169, v169
	v_rcp_f32_e32 v171, v171
	v_rcp_f32_e32 v177, v177
	v_cvt_u32_f32_sdwa v179, v176 dst_sel:WORD_1 dst_unused:UNUSED_PAD src0_sel:DWORD
	v_add_f32_e32 v176, 1.0, v178
	v_rcp_f32_e32 v176, v176
	v_fma_f32 v159, v159, s31, 0.5
	v_fma_f32 v167, v167, s31, 0.5
	v_max_f32_e32 v159, 1.0, v159
	v_fma_f32 v163, v163, s31, 0.5
	v_max_f32_e32 v167, 1.0, v167
	v_fma_f32 v169, v169, s31, 0.5
	v_fma_f32 v171, v171, s31, 0.5
	v_fma_f32 v177, v177, s31, 0.5
	v_cvt_u32_f32_e32 v159, v159
	v_max_f32_e32 v163, 1.0, v163
	v_cvt_u32_f32_e32 v167, v167
	v_max_f32_e32 v169, 1.0, v169
	v_max_f32_e32 v171, 1.0, v171
	v_max_f32_e32 v177, 1.0, v177
	v_fma_f32 v176, v176, s31, 0.5
	v_cvt_u32_f32_e32 v163, v163
	v_cvt_u32_f32_e32 v169, v169
	v_cvt_u32_f32_sdwa v171, v171 dst_sel:WORD_1 dst_unused:UNUSED_PAD src0_sel:DWORD
	v_cvt_u32_f32_sdwa v177, v177 dst_sel:BYTE_3 dst_unused:UNUSED_PAD src0_sel:DWORD
	v_max_f32_e32 v176, 1.0, v176
	v_cvt_u32_f32_sdwa v178, v176 dst_sel:BYTE_3 dst_unused:UNUSED_PAD src0_sel:DWORD
	v_readlane_b32 s22, v252, 34
	v_readlane_b32 s23, v252, 35
	v_lshl_or_b32 v159, v167, 8, v159
	v_or3_b32 v176, v159, v171, v177
	v_lshl_add_u64 v[174:175], s[22:23], 0, v[174:175]
	v_lshl_or_b32 v159, v169, 8, v163
	v_lshl_add_u64 v[174:175], v[174:175], 0, v[172:173]
	v_or3_b32 v177, v159, v179, v178
	global_store_dwordx2 v[174:175], v[176:177], off
	v_mul_f32_e32 v176, v108, v170
	v_mul_f32_e32 v176, 0xbfb8aa3b, v176
	v_exp_f32_e32 v176, v176
	v_mul_f32_e32 v159, v114, v170
	v_mul_f32_e32 v167, v115, v170
	v_mul_f32_e32 v159, 0xbfb8aa3b, v159
	v_mul_f32_e32 v163, v106, v170
	v_mul_f32_e32 v167, 0xbfb8aa3b, v167
	v_mul_f32_e32 v169, v107, v170
	v_mul_f32_e32 v171, v116, v170
	v_add_f32_e32 v176, 1.0, v176
	v_mul_f32_e32 v177, v117, v170
	v_exp_f32_e32 v159, v159
	v_mul_f32_e32 v163, 0xbfb8aa3b, v163
	v_exp_f32_e32 v167, v167
	v_mul_f32_e32 v169, 0xbfb8aa3b, v169
	v_mul_f32_e32 v171, 0xbfb8aa3b, v171
	v_rcp_f32_e32 v176, v176
	v_mul_f32_e32 v177, 0xbfb8aa3b, v177
	v_mul_f32_e32 v178, v109, v170
	v_exp_f32_e32 v163, v163
	v_exp_f32_e32 v169, v169
	v_exp_f32_e32 v171, v171
	v_exp_f32_e32 v177, v177
	v_mul_f32_e32 v178, 0xbfb8aa3b, v178
	v_exp_f32_e32 v178, v178
	v_add_f32_e32 v159, 1.0, v159
	v_add_f32_e32 v167, 1.0, v167
	v_fma_f32 v176, v176, s31, 0.5
	v_rcp_f32_e32 v159, v159
	v_add_f32_e32 v163, 1.0, v163
	v_rcp_f32_e32 v167, v167
	v_add_f32_e32 v169, 1.0, v169
	v_add_f32_e32 v171, 1.0, v171
	v_max_f32_e32 v176, 1.0, v176
	v_add_f32_e32 v177, 1.0, v177
	v_rcp_f32_e32 v163, v163
	v_rcp_f32_e32 v169, v169
	v_rcp_f32_e32 v171, v171
	v_rcp_f32_e32 v177, v177
	v_cvt_u32_f32_sdwa v179, v176 dst_sel:WORD_1 dst_unused:UNUSED_PAD src0_sel:DWORD
	v_add_f32_e32 v176, 1.0, v178
	v_rcp_f32_e32 v176, v176
	v_fma_f32 v159, v159, s31, 0.5
	v_fma_f32 v167, v167, s31, 0.5
	v_max_f32_e32 v159, 1.0, v159
	v_fma_f32 v163, v163, s31, 0.5
	v_max_f32_e32 v167, 1.0, v167
	v_fma_f32 v169, v169, s31, 0.5
	v_fma_f32 v171, v171, s31, 0.5
	v_fma_f32 v177, v177, s31, 0.5
	v_cvt_u32_f32_e32 v159, v159
	v_max_f32_e32 v163, 1.0, v163
	v_cvt_u32_f32_e32 v167, v167
	v_max_f32_e32 v169, 1.0, v169
	v_max_f32_e32 v171, 1.0, v171
	v_max_f32_e32 v177, 1.0, v177
	v_fma_f32 v176, v176, s31, 0.5
	v_cvt_u32_f32_e32 v163, v163
	v_cvt_u32_f32_e32 v169, v169
	v_cvt_u32_f32_sdwa v171, v171 dst_sel:WORD_1 dst_unused:UNUSED_PAD src0_sel:DWORD
	v_cvt_u32_f32_sdwa v177, v177 dst_sel:BYTE_3 dst_unused:UNUSED_PAD src0_sel:DWORD
	v_max_f32_e32 v176, 1.0, v176
	v_cvt_u32_f32_sdwa v178, v176 dst_sel:BYTE_3 dst_unused:UNUSED_PAD src0_sel:DWORD
	v_lshl_or_b32 v159, v167, 8, v159
	v_or3_b32 v176, v159, v171, v177
	v_lshl_or_b32 v159, v169, 8, v163
	v_or3_b32 v177, v159, v179, v178
	global_store_dwordx2 v[174:175], v[176:177], off offset:128
	v_lshlrev_b64 v[174:175], 12, v[164:165]
	v_mul_f32_e32 v159, v118, v166
	v_mul_f32_e32 v165, v119, v166
	v_mul_f32_e32 v159, 0xbfb8aa3b, v159
	v_mul_f32_e32 v163, v110, v166
	v_mul_f32_e32 v165, 0xbfb8aa3b, v165
	v_mul_f32_e32 v167, v111, v166
	v_mul_f32_e32 v169, v120, v166
	v_mul_f32_e32 v176, v121, v166
	v_exp_f32_e32 v159, v159
	v_mul_f32_e32 v163, 0xbfb8aa3b, v163
	v_exp_f32_e32 v165, v165
	v_mul_f32_e32 v167, 0xbfb8aa3b, v167
	v_mul_f32_e32 v169, 0xbfb8aa3b, v169
	v_mul_f32_e32 v171, v112, v166
	v_mul_f32_e32 v176, 0xbfb8aa3b, v176
	v_mul_f32_e32 v177, v113, v166
	v_exp_f32_e32 v163, v163
	v_exp_f32_e32 v167, v167
	v_exp_f32_e32 v169, v169
	v_mul_f32_e32 v171, 0xbfb8aa3b, v171
	v_exp_f32_e32 v176, v176
	v_mul_f32_e32 v177, 0xbfb8aa3b, v177
	v_exp_f32_e32 v171, v171
	v_exp_f32_e32 v177, v177
	v_add_f32_e32 v159, 1.0, v159
	v_add_f32_e32 v165, 1.0, v165
	v_rcp_f32_e32 v159, v159
	v_add_f32_e32 v163, 1.0, v163
	v_rcp_f32_e32 v165, v165
	v_add_f32_e32 v167, 1.0, v167
	v_add_f32_e32 v169, 1.0, v169
	v_add_f32_e32 v176, 1.0, v176
	v_rcp_f32_e32 v163, v163
	v_rcp_f32_e32 v167, v167
	v_rcp_f32_e32 v169, v169
	v_add_f32_e32 v171, 1.0, v171
	v_rcp_f32_e32 v176, v176
	v_add_f32_e32 v177, 1.0, v177
	v_rcp_f32_e32 v171, v171
	v_rcp_f32_e32 v177, v177
	v_fma_f32 v159, v159, s31, 0.5
	v_fma_f32 v165, v165, s31, 0.5
	v_max_f32_e32 v159, 1.0, v159
	v_fma_f32 v163, v163, s31, 0.5
	v_max_f32_e32 v165, 1.0, v165
	v_fma_f32 v167, v167, s31, 0.5
	v_fma_f32 v169, v169, s31, 0.5
	v_fma_f32 v176, v176, s31, 0.5
	v_cvt_u32_f32_e32 v159, v159
	v_max_f32_e32 v163, 1.0, v163
	v_cvt_u32_f32_e32 v165, v165
	v_max_f32_e32 v167, 1.0, v167
	v_max_f32_e32 v169, 1.0, v169
	v_fma_f32 v171, v171, s31, 0.5
	v_max_f32_e32 v176, 1.0, v176
	v_fma_f32 v177, v177, s31, 0.5
	v_cvt_u32_f32_e32 v163, v163
	v_cvt_u32_f32_e32 v167, v167
	v_cvt_u32_f32_sdwa v169, v169 dst_sel:WORD_1 dst_unused:UNUSED_PAD src0_sel:DWORD
	v_max_f32_e32 v171, 1.0, v171
	v_cvt_u32_f32_sdwa v176, v176 dst_sel:BYTE_3 dst_unused:UNUSED_PAD src0_sel:DWORD
	v_max_f32_e32 v177, 1.0, v177
	v_cvt_u32_f32_sdwa v171, v171 dst_sel:WORD_1 dst_unused:UNUSED_PAD src0_sel:DWORD
	v_cvt_u32_f32_sdwa v177, v177 dst_sel:BYTE_3 dst_unused:UNUSED_PAD src0_sel:DWORD
	v_lshl_or_b32 v159, v165, 8, v159
	v_lshl_add_u64 v[174:175], s[22:23], 0, v[174:175]
	v_or3_b32 v176, v159, v169, v176
	v_lshl_or_b32 v159, v167, 8, v163
	v_lshl_add_u64 v[174:175], v[174:175], 0, v[172:173]
	v_or3_b32 v177, v159, v171, v177
	v_mul_f32_e32 v159, v98, v166
	v_mul_f32_e32 v165, v99, v166
	v_mul_f32_e32 v159, 0xbfb8aa3b, v159
	v_mul_f32_e32 v163, v90, v166
	global_store_dwordx2 v[174:175], v[176:177], off
	v_mul_f32_e32 v165, 0xbfb8aa3b, v165
	v_mul_f32_e32 v167, v91, v166
	v_mul_f32_e32 v169, v100, v166
	v_mul_f32_e32 v176, v101, v166
	v_exp_f32_e32 v159, v159
	v_mul_f32_e32 v163, 0xbfb8aa3b, v163
	v_exp_f32_e32 v165, v165
	v_mul_f32_e32 v167, 0xbfb8aa3b, v167
	v_mul_f32_e32 v169, 0xbfb8aa3b, v169
	v_mul_f32_e32 v171, v92, v166
	v_mul_f32_e32 v176, 0xbfb8aa3b, v176
	v_mul_f32_e32 v177, v93, v166
	v_exp_f32_e32 v163, v163
	v_exp_f32_e32 v167, v167
	v_exp_f32_e32 v169, v169
	v_mul_f32_e32 v171, 0xbfb8aa3b, v171
	v_exp_f32_e32 v176, v176
	v_mul_f32_e32 v177, 0xbfb8aa3b, v177
	v_exp_f32_e32 v171, v171
	v_exp_f32_e32 v177, v177
	v_add_f32_e32 v159, 1.0, v159
	v_add_f32_e32 v165, 1.0, v165
	v_rcp_f32_e32 v159, v159
	v_add_f32_e32 v163, 1.0, v163
	v_rcp_f32_e32 v165, v165
	v_add_f32_e32 v167, 1.0, v167
	v_add_f32_e32 v169, 1.0, v169
	v_add_f32_e32 v176, 1.0, v176
	v_rcp_f32_e32 v163, v163
	v_rcp_f32_e32 v167, v167
	v_rcp_f32_e32 v169, v169
	v_add_f32_e32 v171, 1.0, v171
	v_rcp_f32_e32 v176, v176
	v_add_f32_e32 v177, 1.0, v177
	v_rcp_f32_e32 v171, v171
	v_rcp_f32_e32 v177, v177
	v_fma_f32 v159, v159, s31, 0.5
	v_fma_f32 v165, v165, s31, 0.5
	v_max_f32_e32 v159, 1.0, v159
	v_fma_f32 v163, v163, s31, 0.5
	v_max_f32_e32 v165, 1.0, v165
	v_fma_f32 v167, v167, s31, 0.5
	v_fma_f32 v169, v169, s31, 0.5
	v_fma_f32 v176, v176, s31, 0.5
	v_cvt_u32_f32_e32 v159, v159
	v_max_f32_e32 v163, 1.0, v163
	v_cvt_u32_f32_e32 v165, v165
	v_max_f32_e32 v167, 1.0, v167
	v_max_f32_e32 v169, 1.0, v169
	v_fma_f32 v171, v171, s31, 0.5
	v_max_f32_e32 v176, 1.0, v176
	v_fma_f32 v177, v177, s31, 0.5
	v_cvt_u32_f32_e32 v163, v163
	v_cvt_u32_f32_e32 v167, v167
	v_cvt_u32_f32_sdwa v169, v169 dst_sel:WORD_1 dst_unused:UNUSED_PAD src0_sel:DWORD
	v_max_f32_e32 v171, 1.0, v171
	v_cvt_u32_f32_sdwa v176, v176 dst_sel:BYTE_3 dst_unused:UNUSED_PAD src0_sel:DWORD
	v_max_f32_e32 v177, 1.0, v177
	v_cvt_u32_f32_sdwa v171, v171 dst_sel:WORD_1 dst_unused:UNUSED_PAD src0_sel:DWORD
	v_cvt_u32_f32_sdwa v177, v177 dst_sel:BYTE_3 dst_unused:UNUSED_PAD src0_sel:DWORD
	v_lshl_or_b32 v159, v165, 8, v159
	v_or3_b32 v176, v159, v169, v176
	v_lshl_or_b32 v159, v167, 8, v163
	v_or3_b32 v177, v159, v171, v177
	v_mul_f32_e32 v159, v102, v162
	v_mul_f32_e32 v163, v103, v162
	global_store_dwordx2 v[174:175], v[176:177], off offset:128
	v_lshlrev_b64 v[174:175], 12, v[160:161]
	v_mul_f32_e32 v159, 0xbfb8aa3b, v159
	v_mul_f32_e32 v161, v94, v162
	v_mul_f32_e32 v163, 0xbfb8aa3b, v163
	v_mul_f32_e32 v165, v95, v162
	v_mul_f32_e32 v167, v104, v162
	v_mul_f32_e32 v171, v105, v162
	v_exp_f32_e32 v159, v159
	v_mul_f32_e32 v161, 0xbfb8aa3b, v161
	v_exp_f32_e32 v163, v163
	v_mul_f32_e32 v165, 0xbfb8aa3b, v165
	v_mul_f32_e32 v167, 0xbfb8aa3b, v167
	v_mul_f32_e32 v169, v96, v162
	v_mul_f32_e32 v171, 0xbfb8aa3b, v171
	v_mul_f32_e32 v176, v97, v162
	v_exp_f32_e32 v161, v161
	v_exp_f32_e32 v165, v165
	v_exp_f32_e32 v167, v167
	v_mul_f32_e32 v169, 0xbfb8aa3b, v169
	v_exp_f32_e32 v171, v171
	v_mul_f32_e32 v176, 0xbfb8aa3b, v176
	v_exp_f32_e32 v169, v169
	v_exp_f32_e32 v176, v176
	v_add_f32_e32 v159, 1.0, v159
	v_add_f32_e32 v163, 1.0, v163
	v_rcp_f32_e32 v159, v159
	v_add_f32_e32 v161, 1.0, v161
	v_rcp_f32_e32 v163, v163
	v_add_f32_e32 v165, 1.0, v165
	v_add_f32_e32 v167, 1.0, v167
	v_add_f32_e32 v171, 1.0, v171
	v_rcp_f32_e32 v161, v161
	v_rcp_f32_e32 v165, v165
	v_rcp_f32_e32 v167, v167
	v_add_f32_e32 v169, 1.0, v169
	v_rcp_f32_e32 v171, v171
	v_add_f32_e32 v176, 1.0, v176
	v_rcp_f32_e32 v169, v169
	v_rcp_f32_e32 v176, v176
	v_fma_f32 v159, v159, s31, 0.5
	v_fma_f32 v163, v163, s31, 0.5
	v_max_f32_e32 v159, 1.0, v159
	v_fma_f32 v161, v161, s31, 0.5
	v_max_f32_e32 v163, 1.0, v163
	v_fma_f32 v165, v165, s31, 0.5
	v_fma_f32 v167, v167, s31, 0.5
	v_fma_f32 v171, v171, s31, 0.5
	v_cvt_u32_f32_e32 v159, v159
	v_max_f32_e32 v161, 1.0, v161
	v_cvt_u32_f32_e32 v163, v163
	v_max_f32_e32 v165, 1.0, v165
	v_max_f32_e32 v167, 1.0, v167
	v_fma_f32 v169, v169, s31, 0.5
	v_max_f32_e32 v171, 1.0, v171
	v_fma_f32 v176, v176, s31, 0.5
	v_cvt_u32_f32_e32 v161, v161
	v_cvt_u32_f32_e32 v165, v165
	v_cvt_u32_f32_sdwa v167, v167 dst_sel:WORD_1 dst_unused:UNUSED_PAD src0_sel:DWORD
	v_max_f32_e32 v169, 1.0, v169
	v_cvt_u32_f32_sdwa v171, v171 dst_sel:BYTE_3 dst_unused:UNUSED_PAD src0_sel:DWORD
	v_max_f32_e32 v176, 1.0, v176
	v_cvt_u32_f32_sdwa v169, v169 dst_sel:WORD_1 dst_unused:UNUSED_PAD src0_sel:DWORD
	v_cvt_u32_f32_sdwa v177, v176 dst_sel:BYTE_3 dst_unused:UNUSED_PAD src0_sel:DWORD
	v_lshl_or_b32 v159, v163, 8, v159
	v_or3_b32 v176, v159, v167, v171
	v_lshl_or_b32 v159, v165, 8, v161
	v_lshl_add_u64 v[174:175], s[22:23], 0, v[174:175]
	v_or3_b32 v177, v159, v169, v177
	v_mul_f32_e32 v159, v82, v162
	v_mul_f32_e32 v163, v83, v162
	v_lshl_add_u64 v[174:175], v[174:175], 0, v[172:173]
	v_mul_f32_e32 v159, 0xbfb8aa3b, v159
	v_mul_f32_e32 v161, v74, v162
	v_mul_f32_e32 v163, 0xbfb8aa3b, v163
	v_mul_f32_e32 v165, v75, v162
	v_mul_f32_e32 v167, v84, v162
	v_mul_f32_e32 v171, v85, v162
	v_exp_f32_e32 v159, v159
	v_mul_f32_e32 v161, 0xbfb8aa3b, v161
	global_store_dwordx2 v[174:175], v[176:177], off
	v_exp_f32_e32 v163, v163
	v_mul_f32_e32 v165, 0xbfb8aa3b, v165
	v_mul_f32_e32 v167, 0xbfb8aa3b, v167
	v_mul_f32_e32 v169, v76, v162
	v_mul_f32_e32 v171, 0xbfb8aa3b, v171
	v_mul_f32_e32 v176, v77, v162
	v_exp_f32_e32 v161, v161
	v_exp_f32_e32 v165, v165
	v_exp_f32_e32 v167, v167
	v_mul_f32_e32 v169, 0xbfb8aa3b, v169
	v_exp_f32_e32 v171, v171
	v_mul_f32_e32 v176, 0xbfb8aa3b, v176
	v_exp_f32_e32 v169, v169
	v_exp_f32_e32 v176, v176
	v_add_f32_e32 v159, 1.0, v159
	v_add_f32_e32 v163, 1.0, v163
	v_rcp_f32_e32 v159, v159
	v_add_f32_e32 v161, 1.0, v161
	v_rcp_f32_e32 v163, v163
	v_add_f32_e32 v165, 1.0, v165
	v_add_f32_e32 v167, 1.0, v167
	v_add_f32_e32 v171, 1.0, v171
	v_rcp_f32_e32 v161, v161
	v_rcp_f32_e32 v165, v165
	v_rcp_f32_e32 v167, v167
	v_add_f32_e32 v169, 1.0, v169
	v_rcp_f32_e32 v171, v171
	v_add_f32_e32 v176, 1.0, v176
	v_rcp_f32_e32 v169, v169
	v_rcp_f32_e32 v176, v176
	v_fma_f32 v159, v159, s31, 0.5
	v_fma_f32 v163, v163, s31, 0.5
	v_max_f32_e32 v159, 1.0, v159
	v_fma_f32 v161, v161, s31, 0.5
	v_max_f32_e32 v163, 1.0, v163
	v_fma_f32 v165, v165, s31, 0.5
	v_fma_f32 v167, v167, s31, 0.5
	v_fma_f32 v171, v171, s31, 0.5
	v_cvt_u32_f32_e32 v159, v159
	v_max_f32_e32 v161, 1.0, v161
	v_cvt_u32_f32_e32 v163, v163
	v_max_f32_e32 v165, 1.0, v165
	v_max_f32_e32 v167, 1.0, v167
	v_fma_f32 v169, v169, s31, 0.5
	v_max_f32_e32 v171, 1.0, v171
	v_fma_f32 v176, v176, s31, 0.5
	v_cvt_u32_f32_e32 v161, v161
	v_cvt_u32_f32_e32 v165, v165
	v_cvt_u32_f32_sdwa v167, v167 dst_sel:WORD_1 dst_unused:UNUSED_PAD src0_sel:DWORD
	v_max_f32_e32 v169, 1.0, v169
	v_cvt_u32_f32_sdwa v171, v171 dst_sel:BYTE_3 dst_unused:UNUSED_PAD src0_sel:DWORD
	v_max_f32_e32 v176, 1.0, v176
	v_cvt_u32_f32_sdwa v169, v169 dst_sel:WORD_1 dst_unused:UNUSED_PAD src0_sel:DWORD
	v_cvt_u32_f32_sdwa v177, v176 dst_sel:BYTE_3 dst_unused:UNUSED_PAD src0_sel:DWORD
	v_lshl_or_b32 v159, v163, 8, v159
	v_or3_b32 v176, v159, v167, v171
	v_lshl_or_b32 v159, v165, 8, v161
	v_or3_b32 v177, v159, v169, v177
	global_store_dwordx2 v[174:175], v[176:177], off offset:128
	v_lshlrev_b64 v[174:175], 12, v[154:155]
	v_mul_f32_e32 v155, v86, v158
	v_mul_f32_e32 v161, v87, v158
	v_mul_f32_e32 v155, 0xbfb8aa3b, v155
	v_mul_f32_e32 v159, v78, v158
	v_mul_f32_e32 v161, 0xbfb8aa3b, v161
	v_mul_f32_e32 v163, v79, v158
	v_mul_f32_e32 v165, v88, v158
	v_mul_f32_e32 v169, v89, v158
	v_exp_f32_e32 v155, v155
	v_mul_f32_e32 v159, 0xbfb8aa3b, v159
	v_exp_f32_e32 v161, v161
	v_mul_f32_e32 v163, 0xbfb8aa3b, v163
	v_mul_f32_e32 v165, 0xbfb8aa3b, v165
	v_mul_f32_e32 v167, v80, v158
	v_mul_f32_e32 v169, 0xbfb8aa3b, v169
	v_mul_f32_e32 v171, v81, v158
	v_exp_f32_e32 v159, v159
	v_exp_f32_e32 v163, v163
	v_exp_f32_e32 v165, v165
	v_mul_f32_e32 v167, 0xbfb8aa3b, v167
	v_exp_f32_e32 v169, v169
	v_mul_f32_e32 v171, 0xbfb8aa3b, v171
	v_exp_f32_e32 v167, v167
	v_exp_f32_e32 v171, v171
	v_add_f32_e32 v155, 1.0, v155
	v_add_f32_e32 v161, 1.0, v161
	v_rcp_f32_e32 v155, v155
	v_add_f32_e32 v159, 1.0, v159
	v_rcp_f32_e32 v161, v161
	v_add_f32_e32 v163, 1.0, v163
	v_add_f32_e32 v165, 1.0, v165
	v_add_f32_e32 v169, 1.0, v169
	v_rcp_f32_e32 v159, v159
	v_rcp_f32_e32 v163, v163
	v_rcp_f32_e32 v165, v165
	v_add_f32_e32 v167, 1.0, v167
	v_rcp_f32_e32 v169, v169
	v_add_f32_e32 v171, 1.0, v171
	v_rcp_f32_e32 v167, v167
	v_rcp_f32_e32 v171, v171
	v_fma_f32 v155, v155, s31, 0.5
	v_fma_f32 v161, v161, s31, 0.5
	v_max_f32_e32 v155, 1.0, v155
	v_fma_f32 v159, v159, s31, 0.5
	v_max_f32_e32 v161, 1.0, v161
	v_fma_f32 v163, v163, s31, 0.5
	v_fma_f32 v165, v165, s31, 0.5
	v_fma_f32 v169, v169, s31, 0.5
	v_cvt_u32_f32_e32 v155, v155
	v_max_f32_e32 v159, 1.0, v159
	v_cvt_u32_f32_e32 v161, v161
	v_max_f32_e32 v163, 1.0, v163
	v_max_f32_e32 v165, 1.0, v165
	v_fma_f32 v167, v167, s31, 0.5
	v_max_f32_e32 v169, 1.0, v169
	v_fma_f32 v171, v171, s31, 0.5
	v_cvt_u32_f32_e32 v159, v159
	v_cvt_u32_f32_e32 v163, v163
	v_cvt_u32_f32_sdwa v165, v165 dst_sel:WORD_1 dst_unused:UNUSED_PAD src0_sel:DWORD
	v_max_f32_e32 v167, 1.0, v167
	v_cvt_u32_f32_sdwa v169, v169 dst_sel:BYTE_3 dst_unused:UNUSED_PAD src0_sel:DWORD
	v_max_f32_e32 v171, 1.0, v171
	v_cvt_u32_f32_sdwa v167, v167 dst_sel:WORD_1 dst_unused:UNUSED_PAD src0_sel:DWORD
	v_cvt_u32_f32_sdwa v171, v171 dst_sel:BYTE_3 dst_unused:UNUSED_PAD src0_sel:DWORD
	v_lshl_or_b32 v155, v161, 8, v155
	v_or3_b32 v176, v155, v165, v169
	v_lshl_or_b32 v155, v163, 8, v159
	v_or3_b32 v177, v155, v167, v171
	v_mul_f32_e32 v155, v70, v158
	v_mul_f32_e32 v161, v71, v158
	v_mul_f32_e32 v155, 0xbfb8aa3b, v155
	v_mul_f32_e32 v159, v66, v158
	v_mul_f32_e32 v161, 0xbfb8aa3b, v161
	v_mul_f32_e32 v163, v67, v158
	v_mul_f32_e32 v165, v72, v158
	v_mul_f32_e32 v169, v73, v158
	v_exp_f32_e32 v155, v155
	v_mul_f32_e32 v159, 0xbfb8aa3b, v159
	v_exp_f32_e32 v161, v161
	v_mul_f32_e32 v163, 0xbfb8aa3b, v163
	v_mul_f32_e32 v165, 0xbfb8aa3b, v165
	v_mul_f32_e32 v167, v68, v158
	v_mul_f32_e32 v169, 0xbfb8aa3b, v169
	v_mul_f32_e32 v171, v69, v158
	v_exp_f32_e32 v159, v159
	v_exp_f32_e32 v163, v163
	v_exp_f32_e32 v165, v165
	v_mul_f32_e32 v167, 0xbfb8aa3b, v167
	v_exp_f32_e32 v169, v169
	v_mul_f32_e32 v171, 0xbfb8aa3b, v171
	v_exp_f32_e32 v167, v167
	v_exp_f32_e32 v171, v171
	v_add_f32_e32 v155, 1.0, v155
	v_add_f32_e32 v161, 1.0, v161
	v_rcp_f32_e32 v155, v155
	v_add_f32_e32 v159, 1.0, v159
	v_rcp_f32_e32 v161, v161
	v_add_f32_e32 v163, 1.0, v163
	v_add_f32_e32 v165, 1.0, v165
	v_add_f32_e32 v169, 1.0, v169
	v_rcp_f32_e32 v159, v159
	v_rcp_f32_e32 v163, v163
	v_rcp_f32_e32 v165, v165
	v_add_f32_e32 v167, 1.0, v167
	v_rcp_f32_e32 v169, v169
	v_add_f32_e32 v171, 1.0, v171
	v_rcp_f32_e32 v167, v167
	v_rcp_f32_e32 v171, v171
	v_fma_f32 v155, v155, s31, 0.5
	v_fma_f32 v161, v161, s31, 0.5
	v_max_f32_e32 v155, 1.0, v155
	v_fma_f32 v159, v159, s31, 0.5
	v_max_f32_e32 v161, 1.0, v161
	v_fma_f32 v163, v163, s31, 0.5
	v_fma_f32 v165, v165, s31, 0.5
	v_fma_f32 v169, v169, s31, 0.5
	v_cvt_u32_f32_e32 v155, v155
	v_max_f32_e32 v159, 1.0, v159
	v_cvt_u32_f32_e32 v161, v161
	v_max_f32_e32 v163, 1.0, v163
	v_max_f32_e32 v165, 1.0, v165
	v_fma_f32 v167, v167, s31, 0.5
	v_max_f32_e32 v169, 1.0, v169
	v_fma_f32 v171, v171, s31, 0.5
	v_cvt_u32_f32_e32 v159, v159
	v_cvt_u32_f32_e32 v163, v163
	v_cvt_u32_f32_sdwa v165, v165 dst_sel:WORD_1 dst_unused:UNUSED_PAD src0_sel:DWORD
	v_max_f32_e32 v167, 1.0, v167
	v_cvt_u32_f32_sdwa v169, v169 dst_sel:BYTE_3 dst_unused:UNUSED_PAD src0_sel:DWORD
	v_max_f32_e32 v171, 1.0, v171
	v_cvt_u32_f32_sdwa v167, v167 dst_sel:WORD_1 dst_unused:UNUSED_PAD src0_sel:DWORD
	v_cvt_u32_f32_sdwa v171, v171 dst_sel:BYTE_3 dst_unused:UNUSED_PAD src0_sel:DWORD
	v_lshl_add_u64 v[174:175], s[22:23], 0, v[174:175]
	v_lshl_add_u64 v[174:175], v[174:175], 0, v[172:173]
	v_lshl_or_b32 v155, v161, 8, v155
	global_store_dwordx2 v[174:175], v[176:177], off
	v_or3_b32 v176, v155, v165, v169
	v_lshl_or_b32 v155, v163, 8, v159
	v_or3_b32 v177, v155, v167, v171
	v_mul_f32_e32 v155, v62, v152
	v_mul_f32_e32 v159, v63, v152
	global_store_dwordx2 v[174:175], v[176:177], off offset:128
	v_lshlrev_b64 v[174:175], 12, v[156:157]
	v_mul_f32_e32 v155, 0xbfb8aa3b, v155
	v_mul_f32_e32 v157, v58, v152
	v_mul_f32_e32 v159, 0xbfb8aa3b, v159
	v_mul_f32_e32 v161, v59, v152
	v_mul_f32_e32 v163, v64, v152
	v_mul_f32_e32 v167, v65, v152
	v_exp_f32_e32 v155, v155
	v_mul_f32_e32 v157, 0xbfb8aa3b, v157
	v_exp_f32_e32 v159, v159
	v_mul_f32_e32 v161, 0xbfb8aa3b, v161
	v_mul_f32_e32 v163, 0xbfb8aa3b, v163
	v_mul_f32_e32 v165, v60, v152
	v_mul_f32_e32 v167, 0xbfb8aa3b, v167
	v_mul_f32_e32 v169, v61, v152
	v_exp_f32_e32 v157, v157
	v_exp_f32_e32 v161, v161
	v_exp_f32_e32 v163, v163
	v_mul_f32_e32 v165, 0xbfb8aa3b, v165
	v_exp_f32_e32 v167, v167
	v_mul_f32_e32 v169, 0xbfb8aa3b, v169
	v_exp_f32_e32 v165, v165
	v_exp_f32_e32 v169, v169
	v_add_f32_e32 v155, 1.0, v155
	v_add_f32_e32 v159, 1.0, v159
	v_rcp_f32_e32 v155, v155
	v_add_f32_e32 v157, 1.0, v157
	v_rcp_f32_e32 v159, v159
	v_add_f32_e32 v161, 1.0, v161
	v_add_f32_e32 v163, 1.0, v163
	v_add_f32_e32 v167, 1.0, v167
	v_rcp_f32_e32 v157, v157
	v_rcp_f32_e32 v161, v161
	v_rcp_f32_e32 v163, v163
	v_add_f32_e32 v165, 1.0, v165
	v_rcp_f32_e32 v167, v167
	v_add_f32_e32 v169, 1.0, v169
	v_rcp_f32_e32 v165, v165
	v_rcp_f32_e32 v169, v169
	v_fma_f32 v155, v155, s31, 0.5
	v_fma_f32 v159, v159, s31, 0.5
	v_max_f32_e32 v155, 1.0, v155
	v_fma_f32 v157, v157, s31, 0.5
	v_max_f32_e32 v159, 1.0, v159
	v_fma_f32 v161, v161, s31, 0.5
	v_fma_f32 v163, v163, s31, 0.5
	v_fma_f32 v167, v167, s31, 0.5
	v_cvt_u32_f32_e32 v155, v155
	v_max_f32_e32 v157, 1.0, v157
	v_cvt_u32_f32_e32 v159, v159
	v_max_f32_e32 v161, 1.0, v161
	v_max_f32_e32 v163, 1.0, v163
	v_fma_f32 v165, v165, s31, 0.5
	v_max_f32_e32 v167, 1.0, v167
	v_fma_f32 v169, v169, s31, 0.5
	v_cvt_u32_f32_e32 v157, v157
	v_cvt_u32_f32_e32 v161, v161
	v_cvt_u32_f32_sdwa v163, v163 dst_sel:WORD_1 dst_unused:UNUSED_PAD src0_sel:DWORD
	v_max_f32_e32 v165, 1.0, v165
	v_cvt_u32_f32_sdwa v167, v167 dst_sel:BYTE_3 dst_unused:UNUSED_PAD src0_sel:DWORD
	v_max_f32_e32 v169, 1.0, v169
	v_cvt_u32_f32_sdwa v165, v165 dst_sel:WORD_1 dst_unused:UNUSED_PAD src0_sel:DWORD
	v_cvt_u32_f32_sdwa v169, v169 dst_sel:BYTE_3 dst_unused:UNUSED_PAD src0_sel:DWORD
	v_lshl_or_b32 v155, v159, 8, v155
	v_or3_b32 v176, v155, v163, v167
	v_lshl_or_b32 v155, v161, 8, v157
	v_or3_b32 v177, v155, v165, v169
	v_mul_f32_e32 v155, v50, v152
	v_mul_f32_e32 v159, v51, v152
	v_mul_f32_e32 v155, 0xbfb8aa3b, v155
	v_mul_f32_e32 v157, v42, v152
	v_mul_f32_e32 v159, 0xbfb8aa3b, v159
	v_mul_f32_e32 v161, v43, v152
	v_mul_f32_e32 v163, v52, v152
	v_mul_f32_e32 v167, v53, v152
	v_exp_f32_e32 v155, v155
	v_mul_f32_e32 v157, 0xbfb8aa3b, v157
	v_exp_f32_e32 v159, v159
	v_mul_f32_e32 v161, 0xbfb8aa3b, v161
	v_mul_f32_e32 v163, 0xbfb8aa3b, v163
	v_mul_f32_e32 v165, v44, v152
	v_mul_f32_e32 v167, 0xbfb8aa3b, v167
	v_mul_f32_e32 v169, v45, v152
	v_exp_f32_e32 v157, v157
	v_exp_f32_e32 v161, v161
	v_exp_f32_e32 v163, v163
	v_mul_f32_e32 v165, 0xbfb8aa3b, v165
	v_exp_f32_e32 v167, v167
	v_mul_f32_e32 v169, 0xbfb8aa3b, v169
	v_exp_f32_e32 v165, v165
	v_exp_f32_e32 v169, v169
	v_add_f32_e32 v155, 1.0, v155
	v_add_f32_e32 v159, 1.0, v159
	v_rcp_f32_e32 v155, v155
	v_add_f32_e32 v157, 1.0, v157
	v_rcp_f32_e32 v159, v159
	v_add_f32_e32 v161, 1.0, v161
	v_add_f32_e32 v163, 1.0, v163
	v_add_f32_e32 v167, 1.0, v167
	v_rcp_f32_e32 v157, v157
	v_rcp_f32_e32 v161, v161
	v_rcp_f32_e32 v163, v163
	v_add_f32_e32 v165, 1.0, v165
	v_rcp_f32_e32 v167, v167
	v_add_f32_e32 v169, 1.0, v169
	v_rcp_f32_e32 v165, v165
	v_rcp_f32_e32 v169, v169
	v_fma_f32 v155, v155, s31, 0.5
	v_fma_f32 v159, v159, s31, 0.5
	v_max_f32_e32 v155, 1.0, v155
	v_fma_f32 v157, v157, s31, 0.5
	v_max_f32_e32 v159, 1.0, v159
	v_fma_f32 v161, v161, s31, 0.5
	v_fma_f32 v163, v163, s31, 0.5
	v_fma_f32 v167, v167, s31, 0.5
	v_cvt_u32_f32_e32 v155, v155
	v_max_f32_e32 v157, 1.0, v157
	v_cvt_u32_f32_e32 v159, v159
	v_max_f32_e32 v161, 1.0, v161
	v_max_f32_e32 v163, 1.0, v163
	v_fma_f32 v165, v165, s31, 0.5
	v_max_f32_e32 v167, 1.0, v167
	v_fma_f32 v169, v169, s31, 0.5
	v_cvt_u32_f32_e32 v157, v157
	v_cvt_u32_f32_e32 v161, v161
	v_cvt_u32_f32_sdwa v163, v163 dst_sel:WORD_1 dst_unused:UNUSED_PAD src0_sel:DWORD
	v_max_f32_e32 v165, 1.0, v165
	v_cvt_u32_f32_sdwa v167, v167 dst_sel:BYTE_3 dst_unused:UNUSED_PAD src0_sel:DWORD
	v_max_f32_e32 v169, 1.0, v169
	v_cvt_u32_f32_sdwa v165, v165 dst_sel:WORD_1 dst_unused:UNUSED_PAD src0_sel:DWORD
	v_cvt_u32_f32_sdwa v169, v169 dst_sel:BYTE_3 dst_unused:UNUSED_PAD src0_sel:DWORD
	v_lshl_add_u64 v[174:175], s[22:23], 0, v[174:175]
	v_lshl_add_u64 v[174:175], v[174:175], 0, v[172:173]
	v_lshl_or_b32 v155, v159, 8, v155
	global_store_dwordx2 v[174:175], v[176:177], off
	v_or3_b32 v176, v155, v163, v167
	v_lshl_or_b32 v155, v161, 8, v157
	v_or3_b32 v177, v155, v165, v169
	global_store_dwordx2 v[174:175], v[176:177], off offset:128
	v_lshlrev_b64 v[174:175], 12, v[150:151]
	v_mul_f32_e32 v151, v54, v148
	v_mul_f32_e32 v157, v55, v148
	v_mul_f32_e32 v151, 0xbfb8aa3b, v151
	v_mul_f32_e32 v155, v46, v148
	v_mul_f32_e32 v157, 0xbfb8aa3b, v157
	v_mul_f32_e32 v159, v47, v148
	v_mul_f32_e32 v161, v56, v148
	v_mul_f32_e32 v165, v57, v148
	v_exp_f32_e32 v151, v151
	v_mul_f32_e32 v155, 0xbfb8aa3b, v155
	v_exp_f32_e32 v157, v157
	v_mul_f32_e32 v159, 0xbfb8aa3b, v159
	v_mul_f32_e32 v161, 0xbfb8aa3b, v161
	v_mul_f32_e32 v163, v48, v148
	v_mul_f32_e32 v165, 0xbfb8aa3b, v165
	v_mul_f32_e32 v167, v49, v148
	v_exp_f32_e32 v155, v155
	v_exp_f32_e32 v159, v159
	v_exp_f32_e32 v161, v161
	v_mul_f32_e32 v163, 0xbfb8aa3b, v163
	v_exp_f32_e32 v165, v165
	v_mul_f32_e32 v167, 0xbfb8aa3b, v167
	v_exp_f32_e32 v163, v163
	v_exp_f32_e32 v167, v167
	v_add_f32_e32 v151, 1.0, v151
	v_add_f32_e32 v157, 1.0, v157
	v_rcp_f32_e32 v151, v151
	v_add_f32_e32 v155, 1.0, v155
	v_rcp_f32_e32 v157, v157
	v_add_f32_e32 v159, 1.0, v159
	v_add_f32_e32 v161, 1.0, v161
	v_add_f32_e32 v165, 1.0, v165
	v_rcp_f32_e32 v155, v155
	v_rcp_f32_e32 v159, v159
	v_rcp_f32_e32 v161, v161
	v_add_f32_e32 v163, 1.0, v163
	v_rcp_f32_e32 v165, v165
	v_add_f32_e32 v167, 1.0, v167
	v_rcp_f32_e32 v163, v163
	v_rcp_f32_e32 v167, v167
	v_fma_f32 v151, v151, s31, 0.5
	v_fma_f32 v157, v157, s31, 0.5
	v_max_f32_e32 v151, 1.0, v151
	v_fma_f32 v155, v155, s31, 0.5
	v_max_f32_e32 v157, 1.0, v157
	v_fma_f32 v159, v159, s31, 0.5
	v_fma_f32 v161, v161, s31, 0.5
	v_fma_f32 v165, v165, s31, 0.5
	v_cvt_u32_f32_e32 v151, v151
	v_max_f32_e32 v155, 1.0, v155
	v_cvt_u32_f32_e32 v157, v157
	v_max_f32_e32 v159, 1.0, v159
	v_max_f32_e32 v161, 1.0, v161
	v_fma_f32 v163, v163, s31, 0.5
	v_max_f32_e32 v165, 1.0, v165
	v_fma_f32 v167, v167, s31, 0.5
	v_cvt_u32_f32_e32 v155, v155
	v_cvt_u32_f32_e32 v159, v159
	v_cvt_u32_f32_sdwa v161, v161 dst_sel:WORD_1 dst_unused:UNUSED_PAD src0_sel:DWORD
	v_max_f32_e32 v163, 1.0, v163
	v_cvt_u32_f32_sdwa v165, v165 dst_sel:BYTE_3 dst_unused:UNUSED_PAD src0_sel:DWORD
	v_max_f32_e32 v167, 1.0, v167
	v_cvt_u32_f32_sdwa v163, v163 dst_sel:WORD_1 dst_unused:UNUSED_PAD src0_sel:DWORD
	v_cvt_u32_f32_sdwa v167, v167 dst_sel:BYTE_3 dst_unused:UNUSED_PAD src0_sel:DWORD
	v_lshl_or_b32 v151, v157, 8, v151
	v_or3_b32 v176, v151, v161, v165
	v_lshl_or_b32 v151, v159, 8, v155
	v_or3_b32 v177, v151, v163, v167
	v_mul_f32_e32 v151, v34, v148
	v_mul_f32_e32 v157, v35, v148
	v_mul_f32_e32 v151, 0xbfb8aa3b, v151
	v_mul_f32_e32 v155, v26, v148
	v_mul_f32_e32 v157, 0xbfb8aa3b, v157
	v_mul_f32_e32 v159, v27, v148
	v_mul_f32_e32 v161, v36, v148
	v_mul_f32_e32 v165, v37, v148
	v_exp_f32_e32 v151, v151
	v_mul_f32_e32 v155, 0xbfb8aa3b, v155
	v_exp_f32_e32 v157, v157
	v_mul_f32_e32 v159, 0xbfb8aa3b, v159
	v_mul_f32_e32 v161, 0xbfb8aa3b, v161
	v_mul_f32_e32 v163, v28, v148
	v_mul_f32_e32 v165, 0xbfb8aa3b, v165
	v_mul_f32_e32 v167, v29, v148
	v_exp_f32_e32 v155, v155
	v_exp_f32_e32 v159, v159
	v_exp_f32_e32 v161, v161
	v_mul_f32_e32 v163, 0xbfb8aa3b, v163
	v_exp_f32_e32 v165, v165
	v_mul_f32_e32 v167, 0xbfb8aa3b, v167
	v_exp_f32_e32 v163, v163
	v_exp_f32_e32 v167, v167
	v_add_f32_e32 v151, 1.0, v151
	v_add_f32_e32 v157, 1.0, v157
	v_rcp_f32_e32 v151, v151
	v_add_f32_e32 v155, 1.0, v155
	v_rcp_f32_e32 v157, v157
	v_add_f32_e32 v159, 1.0, v159
	v_add_f32_e32 v161, 1.0, v161
	v_add_f32_e32 v165, 1.0, v165
	v_rcp_f32_e32 v155, v155
	v_rcp_f32_e32 v159, v159
	v_rcp_f32_e32 v161, v161
	v_add_f32_e32 v163, 1.0, v163
	v_rcp_f32_e32 v165, v165
	v_add_f32_e32 v167, 1.0, v167
	v_rcp_f32_e32 v163, v163
	v_rcp_f32_e32 v167, v167
	v_fma_f32 v151, v151, s31, 0.5
	v_fma_f32 v157, v157, s31, 0.5
	v_max_f32_e32 v151, 1.0, v151
	v_fma_f32 v155, v155, s31, 0.5
	v_max_f32_e32 v157, 1.0, v157
	v_fma_f32 v159, v159, s31, 0.5
	v_fma_f32 v161, v161, s31, 0.5
	v_fma_f32 v165, v165, s31, 0.5
	v_cvt_u32_f32_e32 v151, v151
	v_max_f32_e32 v155, 1.0, v155
	v_cvt_u32_f32_e32 v157, v157
	v_max_f32_e32 v159, 1.0, v159
	v_max_f32_e32 v161, 1.0, v161
	v_fma_f32 v163, v163, s31, 0.5
	v_max_f32_e32 v165, 1.0, v165
	v_fma_f32 v167, v167, s31, 0.5
	v_cvt_u32_f32_e32 v155, v155
	v_cvt_u32_f32_e32 v159, v159
	v_cvt_u32_f32_sdwa v161, v161 dst_sel:WORD_1 dst_unused:UNUSED_PAD src0_sel:DWORD
	v_max_f32_e32 v163, 1.0, v163
	v_cvt_u32_f32_sdwa v165, v165 dst_sel:BYTE_3 dst_unused:UNUSED_PAD src0_sel:DWORD
	v_max_f32_e32 v167, 1.0, v167
	v_cvt_u32_f32_sdwa v163, v163 dst_sel:WORD_1 dst_unused:UNUSED_PAD src0_sel:DWORD
	v_cvt_u32_f32_sdwa v167, v167 dst_sel:BYTE_3 dst_unused:UNUSED_PAD src0_sel:DWORD
	v_lshl_add_u64 v[174:175], s[22:23], 0, v[174:175]
	v_lshl_add_u64 v[174:175], v[174:175], 0, v[172:173]
	v_lshl_or_b32 v151, v157, 8, v151
	global_store_dwordx2 v[174:175], v[176:177], off
	v_or3_b32 v176, v151, v161, v165
	v_lshl_or_b32 v151, v159, 8, v155
	v_or3_b32 v177, v151, v163, v167
	global_store_dwordx2 v[174:175], v[176:177], off offset:128
	v_lshlrev_b64 v[174:175], 12, v[146:147]
	v_mul_f32_e32 v147, v38, v144
	v_mul_f32_e32 v155, v39, v144
	v_mul_f32_e32 v147, 0xbfb8aa3b, v147
	v_mul_f32_e32 v151, v30, v144
	v_mul_f32_e32 v155, 0xbfb8aa3b, v155
	v_mul_f32_e32 v157, v31, v144
	v_mul_f32_e32 v159, v40, v144
	v_mul_f32_e32 v163, v41, v144
	v_exp_f32_e32 v147, v147
	v_mul_f32_e32 v151, 0xbfb8aa3b, v151
	v_exp_f32_e32 v155, v155
	v_mul_f32_e32 v157, 0xbfb8aa3b, v157
	v_mul_f32_e32 v159, 0xbfb8aa3b, v159
	v_mul_f32_e32 v161, v32, v144
	v_mul_f32_e32 v163, 0xbfb8aa3b, v163
	v_mul_f32_e32 v165, v33, v144
	v_exp_f32_e32 v151, v151
	v_exp_f32_e32 v157, v157
	v_exp_f32_e32 v159, v159
	v_mul_f32_e32 v161, 0xbfb8aa3b, v161
	v_exp_f32_e32 v163, v163
	v_mul_f32_e32 v165, 0xbfb8aa3b, v165
	v_exp_f32_e32 v161, v161
	v_exp_f32_e32 v165, v165
	v_add_f32_e32 v147, 1.0, v147
	v_add_f32_e32 v155, 1.0, v155
	v_rcp_f32_e32 v147, v147
	v_add_f32_e32 v151, 1.0, v151
	v_rcp_f32_e32 v155, v155
	v_add_f32_e32 v157, 1.0, v157
	v_add_f32_e32 v159, 1.0, v159
	v_add_f32_e32 v163, 1.0, v163
	v_rcp_f32_e32 v151, v151
	v_rcp_f32_e32 v157, v157
	v_rcp_f32_e32 v159, v159
	v_add_f32_e32 v161, 1.0, v161
	v_rcp_f32_e32 v163, v163
	v_add_f32_e32 v165, 1.0, v165
	v_rcp_f32_e32 v161, v161
	v_rcp_f32_e32 v165, v165
	v_fma_f32 v147, v147, s31, 0.5
	v_fma_f32 v155, v155, s31, 0.5
	v_max_f32_e32 v147, 1.0, v147
	v_fma_f32 v151, v151, s31, 0.5
	v_max_f32_e32 v155, 1.0, v155
	v_fma_f32 v157, v157, s31, 0.5
	v_fma_f32 v159, v159, s31, 0.5
	v_fma_f32 v163, v163, s31, 0.5
	v_cvt_u32_f32_e32 v147, v147
	v_max_f32_e32 v151, 1.0, v151
	v_cvt_u32_f32_e32 v155, v155
	v_max_f32_e32 v157, 1.0, v157
	v_max_f32_e32 v159, 1.0, v159
	v_fma_f32 v161, v161, s31, 0.5
	v_max_f32_e32 v163, 1.0, v163
	v_fma_f32 v165, v165, s31, 0.5
	v_cvt_u32_f32_e32 v151, v151
	v_cvt_u32_f32_e32 v157, v157
	v_cvt_u32_f32_sdwa v159, v159 dst_sel:WORD_1 dst_unused:UNUSED_PAD src0_sel:DWORD
	v_max_f32_e32 v161, 1.0, v161
	v_cvt_u32_f32_sdwa v163, v163 dst_sel:BYTE_3 dst_unused:UNUSED_PAD src0_sel:DWORD
	v_max_f32_e32 v165, 1.0, v165
	v_cvt_u32_f32_sdwa v161, v161 dst_sel:WORD_1 dst_unused:UNUSED_PAD src0_sel:DWORD
	v_cvt_u32_f32_sdwa v165, v165 dst_sel:BYTE_3 dst_unused:UNUSED_PAD src0_sel:DWORD
	v_lshl_or_b32 v147, v155, 8, v147
	v_or3_b32 v176, v147, v159, v163
	v_lshl_or_b32 v147, v157, 8, v151
	v_or3_b32 v177, v147, v161, v165
	v_mul_f32_e32 v147, v18, v144
	v_mul_f32_e32 v155, v19, v144
	v_mul_f32_e32 v147, 0xbfb8aa3b, v147
	v_mul_f32_e32 v151, v8, v144
	v_mul_f32_e32 v155, 0xbfb8aa3b, v155
	v_mul_f32_e32 v157, v9, v144
	v_mul_f32_e32 v159, v20, v144
	v_mul_f32_e32 v163, v21, v144
	v_exp_f32_e32 v147, v147
	v_mul_f32_e32 v151, 0xbfb8aa3b, v151
	v_exp_f32_e32 v155, v155
	v_mul_f32_e32 v157, 0xbfb8aa3b, v157
	v_mul_f32_e32 v159, 0xbfb8aa3b, v159
	v_mul_f32_e32 v161, v10, v144
	v_mul_f32_e32 v163, 0xbfb8aa3b, v163
	v_mul_f32_e32 v165, v11, v144
	v_exp_f32_e32 v151, v151
	v_exp_f32_e32 v157, v157
	v_exp_f32_e32 v159, v159
	v_mul_f32_e32 v161, 0xbfb8aa3b, v161
	v_exp_f32_e32 v163, v163
	v_mul_f32_e32 v165, 0xbfb8aa3b, v165
	v_exp_f32_e32 v161, v161
	v_exp_f32_e32 v165, v165
	v_add_f32_e32 v147, 1.0, v147
	v_add_f32_e32 v155, 1.0, v155
	v_rcp_f32_e32 v147, v147
	v_add_f32_e32 v151, 1.0, v151
	v_rcp_f32_e32 v155, v155
	v_add_f32_e32 v157, 1.0, v157
	v_add_f32_e32 v159, 1.0, v159
	v_add_f32_e32 v163, 1.0, v163
	v_rcp_f32_e32 v151, v151
	v_rcp_f32_e32 v157, v157
	v_rcp_f32_e32 v159, v159
	v_add_f32_e32 v161, 1.0, v161
	v_rcp_f32_e32 v163, v163
	v_add_f32_e32 v165, 1.0, v165
	v_rcp_f32_e32 v161, v161
	v_rcp_f32_e32 v165, v165
	v_fma_f32 v147, v147, s31, 0.5
	v_fma_f32 v155, v155, s31, 0.5
	v_max_f32_e32 v147, 1.0, v147
	v_fma_f32 v151, v151, s31, 0.5
	v_max_f32_e32 v155, 1.0, v155
	v_fma_f32 v157, v157, s31, 0.5
	v_fma_f32 v159, v159, s31, 0.5
	v_fma_f32 v163, v163, s31, 0.5
	v_cvt_u32_f32_e32 v147, v147
	v_max_f32_e32 v151, 1.0, v151
	v_cvt_u32_f32_e32 v155, v155
	v_max_f32_e32 v157, 1.0, v157
	v_max_f32_e32 v159, 1.0, v159
	v_fma_f32 v161, v161, s31, 0.5
	v_max_f32_e32 v163, 1.0, v163
	v_fma_f32 v165, v165, s31, 0.5
	v_cvt_u32_f32_e32 v151, v151
	v_cvt_u32_f32_e32 v157, v157
	v_cvt_u32_f32_sdwa v159, v159 dst_sel:WORD_1 dst_unused:UNUSED_PAD src0_sel:DWORD
	v_max_f32_e32 v161, 1.0, v161
	v_cvt_u32_f32_sdwa v163, v163 dst_sel:BYTE_3 dst_unused:UNUSED_PAD src0_sel:DWORD
	v_max_f32_e32 v165, 1.0, v165
	v_cvt_u32_f32_sdwa v161, v161 dst_sel:WORD_1 dst_unused:UNUSED_PAD src0_sel:DWORD
	v_cvt_u32_f32_sdwa v165, v165 dst_sel:BYTE_3 dst_unused:UNUSED_PAD src0_sel:DWORD
	v_lshl_add_u64 v[174:175], s[22:23], 0, v[174:175]
	v_lshl_add_u64 v[174:175], v[174:175], 0, v[172:173]
	v_lshl_or_b32 v147, v155, 8, v147
	global_store_dwordx2 v[174:175], v[176:177], off
	v_or3_b32 v176, v147, v159, v163
	v_lshl_or_b32 v147, v157, 8, v151
	v_or3_b32 v177, v147, v161, v165
	global_store_dwordx2 v[174:175], v[176:177], off offset:128
	v_lshlrev_b64 v[174:175], 12, v[142:143]
	v_mul_f32_e32 v143, v22, v140
	v_mul_f32_e32 v151, v23, v140
	v_mul_f32_e32 v143, 0xbfb8aa3b, v143
	v_mul_f32_e32 v147, v12, v140
	v_mul_f32_e32 v151, 0xbfb8aa3b, v151
	v_mul_f32_e32 v155, v13, v140
	v_mul_f32_e32 v157, v24, v140
	v_mul_f32_e32 v161, v25, v140
	v_exp_f32_e32 v143, v143
	v_mul_f32_e32 v147, 0xbfb8aa3b, v147
	v_exp_f32_e32 v151, v151
	v_mul_f32_e32 v155, 0xbfb8aa3b, v155
	v_mul_f32_e32 v157, 0xbfb8aa3b, v157
	v_mul_f32_e32 v159, v14, v140
	v_mul_f32_e32 v161, 0xbfb8aa3b, v161
	v_mul_f32_e32 v163, v15, v140
	v_exp_f32_e32 v147, v147
	v_exp_f32_e32 v155, v155
	v_exp_f32_e32 v157, v157
	v_mul_f32_e32 v159, 0xbfb8aa3b, v159
	v_exp_f32_e32 v161, v161
	v_mul_f32_e32 v163, 0xbfb8aa3b, v163
	v_exp_f32_e32 v159, v159
	v_exp_f32_e32 v163, v163
	v_add_f32_e32 v143, 1.0, v143
	v_add_f32_e32 v151, 1.0, v151
	v_rcp_f32_e32 v143, v143
	v_add_f32_e32 v147, 1.0, v147
	v_rcp_f32_e32 v151, v151
	v_add_f32_e32 v155, 1.0, v155
	v_add_f32_e32 v157, 1.0, v157
	v_add_f32_e32 v161, 1.0, v161
	v_rcp_f32_e32 v147, v147
	v_rcp_f32_e32 v155, v155
	v_rcp_f32_e32 v157, v157
	v_add_f32_e32 v159, 1.0, v159
	v_rcp_f32_e32 v161, v161
	v_add_f32_e32 v163, 1.0, v163
	v_rcp_f32_e32 v159, v159
	v_rcp_f32_e32 v163, v163
	v_fma_f32 v143, v143, s31, 0.5
	v_fma_f32 v151, v151, s31, 0.5
	v_max_f32_e32 v143, 1.0, v143
	v_fma_f32 v147, v147, s31, 0.5
	v_max_f32_e32 v151, 1.0, v151
	v_fma_f32 v155, v155, s31, 0.5
	v_fma_f32 v157, v157, s31, 0.5
	v_fma_f32 v161, v161, s31, 0.5
	v_cvt_u32_f32_e32 v143, v143
	v_max_f32_e32 v147, 1.0, v147
	v_cvt_u32_f32_e32 v151, v151
	v_max_f32_e32 v155, 1.0, v155
	v_max_f32_e32 v157, 1.0, v157
	v_fma_f32 v159, v159, s31, 0.5
	v_max_f32_e32 v161, 1.0, v161
	v_fma_f32 v163, v163, s31, 0.5
	v_cvt_u32_f32_e32 v147, v147
	v_cvt_u32_f32_e32 v155, v155
	v_cvt_u32_f32_sdwa v157, v157 dst_sel:WORD_1 dst_unused:UNUSED_PAD src0_sel:DWORD
	v_max_f32_e32 v159, 1.0, v159
	v_cvt_u32_f32_sdwa v161, v161 dst_sel:BYTE_3 dst_unused:UNUSED_PAD src0_sel:DWORD
	v_max_f32_e32 v163, 1.0, v163
	v_cvt_u32_f32_sdwa v159, v159 dst_sel:WORD_1 dst_unused:UNUSED_PAD src0_sel:DWORD
	v_cvt_u32_f32_sdwa v163, v163 dst_sel:BYTE_3 dst_unused:UNUSED_PAD src0_sel:DWORD
	v_lshl_or_b32 v143, v151, 8, v143
	v_or3_b32 v176, v143, v157, v161
	v_lshl_or_b32 v143, v155, 8, v147
	v_or3_b32 v177, v143, v159, v163
	v_mul_f32_e32 v143, v4, v140
	v_mul_f32_e32 v151, v5, v140
	v_mul_f32_e32 v143, 0xbfb8aa3b, v143
	v_mul_f32_e32 v147, v0, v140
	v_mul_f32_e32 v151, 0xbfb8aa3b, v151
	v_mul_f32_e32 v155, v1, v140
	v_mul_f32_e32 v157, v6, v140
	v_mul_f32_e32 v161, v7, v140
	v_exp_f32_e32 v143, v143
	v_mul_f32_e32 v147, 0xbfb8aa3b, v147
	v_exp_f32_e32 v151, v151
	v_mul_f32_e32 v155, 0xbfb8aa3b, v155
	v_mul_f32_e32 v157, 0xbfb8aa3b, v157
	v_mul_f32_e32 v159, v2, v140
	v_mul_f32_e32 v161, 0xbfb8aa3b, v161
	v_mul_f32_e32 v163, v3, v140
	v_exp_f32_e32 v147, v147
	v_exp_f32_e32 v155, v155
	v_exp_f32_e32 v157, v157
	v_mul_f32_e32 v159, 0xbfb8aa3b, v159
	v_exp_f32_e32 v161, v161
	v_mul_f32_e32 v163, 0xbfb8aa3b, v163
	v_exp_f32_e32 v159, v159
	v_exp_f32_e32 v163, v163
	v_add_f32_e32 v143, 1.0, v143
	v_add_f32_e32 v151, 1.0, v151
	v_rcp_f32_e32 v143, v143
	v_add_f32_e32 v147, 1.0, v147
	v_rcp_f32_e32 v151, v151
	v_add_f32_e32 v155, 1.0, v155
	v_add_f32_e32 v157, 1.0, v157
	v_add_f32_e32 v161, 1.0, v161
	v_rcp_f32_e32 v147, v147
	v_rcp_f32_e32 v155, v155
	v_rcp_f32_e32 v157, v157
	v_add_f32_e32 v159, 1.0, v159
	v_rcp_f32_e32 v161, v161
	v_add_f32_e32 v163, 1.0, v163
	v_rcp_f32_e32 v159, v159
	v_rcp_f32_e32 v163, v163
	v_fma_f32 v143, v143, s31, 0.5
	v_fma_f32 v151, v151, s31, 0.5
	v_max_f32_e32 v143, 1.0, v143
	v_fma_f32 v147, v147, s31, 0.5
	v_max_f32_e32 v151, 1.0, v151
	v_fma_f32 v155, v155, s31, 0.5
	v_fma_f32 v157, v157, s31, 0.5
	v_fma_f32 v161, v161, s31, 0.5
	v_cvt_u32_f32_e32 v143, v143
	v_max_f32_e32 v147, 1.0, v147
	v_cvt_u32_f32_e32 v151, v151
	v_max_f32_e32 v155, 1.0, v155
	v_max_f32_e32 v157, 1.0, v157
	v_fma_f32 v159, v159, s31, 0.5
	v_max_f32_e32 v161, 1.0, v161
	v_fma_f32 v163, v163, s31, 0.5
	v_cvt_u32_f32_e32 v147, v147
	v_cvt_u32_f32_e32 v155, v155
	v_cvt_u32_f32_sdwa v157, v157 dst_sel:WORD_1 dst_unused:UNUSED_PAD src0_sel:DWORD
	v_max_f32_e32 v159, 1.0, v159
	v_cvt_u32_f32_sdwa v161, v161 dst_sel:BYTE_3 dst_unused:UNUSED_PAD src0_sel:DWORD
	v_max_f32_e32 v163, 1.0, v163
	v_cvt_u32_f32_sdwa v159, v159 dst_sel:WORD_1 dst_unused:UNUSED_PAD src0_sel:DWORD
	v_cvt_u32_f32_sdwa v163, v163 dst_sel:BYTE_3 dst_unused:UNUSED_PAD src0_sel:DWORD
	v_lshl_add_u64 v[174:175], s[22:23], 0, v[174:175]
	v_lshl_add_u64 v[174:175], v[174:175], 0, v[172:173]
	v_lshl_or_b32 v143, v151, 8, v143
	global_store_dwordx2 v[174:175], v[176:177], off
	v_or3_b32 v176, v143, v157, v161
	v_lshl_or_b32 v143, v155, 8, v147
	v_or3_b32 v177, v143, v159, v163
	s_mov_b64 s[22:23], 0
	global_store_dwordx2 v[174:175], v[176:177], off offset:128
	s_branch .LBB0_674
